# EPI_M GEMM k-loop rewritten as an 8-phase schedule (half-tile staging per phase, counted vmcnt, two wave groups one barrier apart), no setprio
# speedup vs baseline: 1.0114x; 1.0095x over previous
; template <bool SWAP>
; DI void gemm_mainloop(f32x16 (&acc)[4][2], const u16* __restrict__ A, int lda, int rlo, int rhi,
;                       const u16* __restrict__ B, int ldb, int K, char* lds, const u16* zero_line) {
;     ...
;   const int gch = (lc ^ ((lr >> 1) & 7)) * 8;
;   const u16* ap = A + (ptrdiff_t)lr * lda + gch;
;   const u16* bp = B + (ptrdiff_t)lr * ldb + gch;
;   const int nk = K >> 6;
;   typedef __attribute__((address_space(3))) unsigned lds_u32;
;   auto glds = [&](int kt, int st) {
;     char* as_ = lds + st * 65536 + tid * 16;
; #pragma unroll
;     for (int i = 0; i < 4; ++i) {
;       const int rr = lr + 64 * i;
;       const u16* srca = (rr >= rlo && rr < rhi) ? (ap + (ptrdiff_t)(64 * i) * lda + kt * 64) : (zero_line + lc * 8);
;       __builtin_amdgcn_global_load_lds((const unsigned*)srca, (lds_u32*)(as_ + i * 8192), 16, 0, 0);
;       __builtin_amdgcn_global_load_lds((const unsigned*)(bp + (ptrdiff_t)(64 * i) * ldb + kt * 64), (lds_u32*)(as_ + 32768 + i * 8192), 16, 0, 0);
;     }
;   };
;   const int sw = (r >> 1) & 7;
;   const int arow_off = (wm * 128 + r) * 128;
;   const int brow_off = 32768 + (wn * 64 + r) * 128;
;   __syncthreads();
;   glds(0, 0);
;   asm volatile("s_waitcnt vmcnt(0)" ::: "memory");
;   __syncthreads();
; template <int EPI>
; DI void phase_gemm(const Params& p, const GemmArgs& ga, char* lds) {
;     ...
;   for (int it = 0; it * (int)gridDim.x < total; ++it) {
;     const int lt = logical_index(it);
;     if (lt >= total) continue;
;     int mt, nt;
;     tile_mn(lt, Mt, ga.Nt, mt, nt);
;     int bb, tokbase, S, pos0, rlo = 0, rhi = 256;
;     if (EPI == EPI_UP) {
;       bb = 0; tokbase = 0; S = NTOK;
;       pos0 = 254 * mt - 1;
;       rlo = (mt == 0) ? 1 : 0;
;       rhi = NTOK - pos0; if (rhi > 256) rhi = 256;
;     } else {
;       seq_of_token(mt * 256, bb, tokbase, S);
;       pos0 = mt * 256 - tokbase;
;     }
;     const u16* A = ga.A + (ptrdiff_t)(tokbase + pos0) * ga.lda;
;     const u16* B = ga.Bt + (size_t)(nt * 256) * ga.K;
.LBB0_244:
	s_add_i32 s6, s6, s27
	s_cmpk_gt_i32 s6, 0x2ff
	s_cbranch_scc1 .LBB0_243
	s_ashr_i32 s7, s6, 31
	s_lshr_b32 s7, s7, 27
	s_add_i32 s7, s6, s7
	s_ashr_i32 s35, s7, 5
	s_andn2_b32 s7, s7, 31
	s_sub_i32 s6, s6, s7
	s_ashr_i32 s7, s6, 31
	s_lshr_b32 s7, s7, 29
	s_add_i32 s7, s6, s7
	s_ashr_i32 s7, s7, 3
	s_lshl_b32 s8, s35, 11
	s_lshl_b32 s6, s6, 8
	s_lshl_b32 s24, s7, 8
	s_add_i32 s6, s6, s8
	s_lshl_b32 s36, s7, 11
	s_ashr_i32 s25, s24, 31
	s_sub_i32 s34, s6, s36
	s_mul_i32 s6, s25, s98
	s_mul_hi_u32 s7, s24, s98
	s_add_i32 s7, s7, s6
	s_mul_i32 s6, s24, s98
	s_lshl_b64 s[6:7], s[6:7], 1
	s_add_u32 s6, s16, s6
	v_mov_b32_e32 v10, v204
	s_addc_u32 s7, s17, s7
	s_ashr_i32 s8, s34, 31
	s_mul_i32 s8, s8, s98
	v_ashrrev_i32_e32 v2, 3, v10
	s_mul_hi_u32 s9, s34, s98
	v_mad_u64_u32 v[4:5], s[10:11], v2, s98, 0
	s_add_i32 s9, s9, s8
	s_mul_i32 s8, s34, s98
	v_ashrrev_i32_e32 v3, 31, v2
	v_mov_b32_e32 v0, v5
	s_lshl_b64 s[8:9], s[8:9], 1
	v_lshrrev_b32_e32 v12, 1, v2
	v_mad_u64_u32 v[6:7], s[10:11], v3, s98, v[0:1]
	s_add_u32 s8, s12, s8
	v_xor_b32_e32 v9, v12, v10
	v_mov_b32_e32 v5, v6
	s_addc_u32 s9, s13, s9
	v_lshlrev_b64 v[4:5], 1, v[4:5]
	v_lshlrev_b32_e32 v0, 4, v9
	v_and_b32_e32 v8, 31, v10
	v_lshl_add_u64 v[6:7], s[8:9], 0, v[4:5]
	v_and_b32_e32 v0, 0x70, v0
	v_lshl_add_u64 v[4:5], s[6:7], 0, v[4:5]
	v_lshrrev_b32_e32 v13, 1, v10
	v_lshl_add_u64 v[6:7], v[6:7], 0, v[0:1]
	v_lshl_add_u64 v[4:5], v[4:5], 0, v[0:1]
	v_and_or_b32 v0, v13, s51, v8
	v_lshlrev_b32_e32 v203, 7, v0
	v_lshlrev_b32_e32 v0, 7, v10
	v_lshlrev_b32_e32 v226, 4, v10
	v_and_b32_e32 v202, 0x6f80, v0
	v_and_b32_e32 v0, 0x70, v226
	v_add_u32_e32 v15, 0x8000, v226
	v_lshl_add_u64 v[180:181], s[80:81], 0, v[0:1]
	v_cmp_gt_u32_e32 vcc, s50, v2
	v_readfirstlane_b32 s6, v226
	s_mov_b32 m0, s6
	v_cndmask_b32_e32 v9, v181, v7, vcc
	v_cndmask_b32_e32 v8, v180, v6, vcc
	v_readfirstlane_b32 s6, v15
	v_add_u32_e32 v0, 64, v2
	s_barrier
	s_mov_b32 m0, s6
	v_cmp_gt_u32_e64 s[6:7], s50, v0
	v_add_u32_e32 v0, 0x2000, v226
	v_lshl_add_u64 v[6:7], v[6:7], 0, s[18:19]
	v_readfirstlane_b32 s8, v0
	v_add_u32_e32 v0, 0xa000, v226
	v_cndmask_b32_e64 v9, v181, v7, s[6:7]
	v_cndmask_b32_e64 v8, v180, v6, s[6:7]
	s_mov_b32 m0, s8
	v_readfirstlane_b32 s8, v0
	v_add_u32_e32 v0, 0x80, v2
	s_mov_b32 m0, s8
	v_cmp_gt_u32_e64 s[8:9], s50, v0
	v_add_u32_e32 v0, 0x4000, v226
	v_lshl_add_u64 v[4:5], v[4:5], 0, s[18:19]
	v_lshl_add_u64 v[6:7], v[6:7], 0, s[18:19]
	v_readfirstlane_b32 s10, v0
	v_add_u32_e32 v0, 0xc000, v226
	v_cndmask_b32_e64 v9, v181, v7, s[8:9]
	v_cndmask_b32_e64 v8, v180, v6, s[8:9]
	s_mov_b32 m0, s10
	v_readfirstlane_b32 s10, v0
	v_add_u32_e32 v0, 0xc0, v2
	s_mov_b32 m0, s10
	v_cmp_gt_u32_e64 s[10:11], s50, v0
	v_add_u32_e32 v0, 0x6000, v226
	v_lshl_add_u64 v[4:5], v[4:5], 0, s[18:19]
	v_lshl_add_u64 v[6:7], v[6:7], 0, s[18:19]
	v_readfirstlane_b32 s37, v0
	v_add_u32_e32 v0, 0xe000, v226
	v_cndmask_b32_e64 v7, v181, v7, s[10:11]
	v_cndmask_b32_e64 v6, v180, v6, s[10:11]
	s_mov_b32 m0, s37
	v_readfirstlane_b32 s37, v0
	v_lshl_add_u64 v[4:5], v[4:5], 0, s[18:19]
	s_mov_b32 m0, s37
	s_sub_i32 s36, s29, s36
	s_mulk_i32 s35, 0x1800
	s_sub_i32 s36, s36, s35
	s_ashr_i32 s37, s36, 31
	v_lshlrev_b64 v[2:3], 1, v[2:3]
	s_lshl_b64 s[36:37], s[36:37], 1
	v_lshl_add_u64 v[4:5], v[2:3], 0, s[36:37]
	v_mov_b64_e32 v[6:7], s[20:21]
	v_mad_u64_u32 v[182:183], s[38:39], s98, v4, v[6:7]
	v_mov_b32_e32 v4, v183
	v_mad_u64_u32 v[4:5], s[38:39], s98, v5, v[4:5]
	s_lshl_b64 s[38:39], s[24:25], 1
	v_bfe_u32 v11, v10, 5, 1
	v_mov_b32_e32 v183, v4
	v_lshl_add_u64 v[4:5], v[2:3], 0, s[38:39]
	v_mov_b64_e32 v[8:9], s[22:23]
	v_bfe_u32 v14, v10, 1, 3
	v_bitop3_b32 v0, v13, v11, 7 bitop3:0x6c
	v_mad_u64_u32 v[186:187], s[40:41], s98, v4, v[8:9]
	v_lshlrev_b32_e32 v228, 4, v0
	v_bitop3_b32 v0, v11, v14, 2 bitop3:0x36
	v_mov_b32_e32 v4, v187
	v_lshlrev_b32_e32 v227, 4, v0
	v_bitop3_b32 v0, v11, v14, 4 bitop3:0x36
	v_mad_u64_u32 v[4:5], s[40:41], s98, v5, v[4:5]
	v_lshlrev_b32_e32 v201, 4, v0
	v_bitop3_b32 v0, v11, v14, 6 bitop3:0x36
	v_mov_b32_e32 v187, v4
	v_lshl_add_u64 v[4:5], v[2:3], 0, s[4:5]
	v_lshlrev_b32_e32 v179, 4, v0
	v_bitop3_b32 v0, v12, 7, v10 bitop3:0x48
	v_lshl_add_u64 v[10:11], v[4:5], 0, s[36:37]
	v_lshl_add_u64 v[4:5], v[4:5], 0, s[38:39]
	v_mad_u64_u32 v[188:189], s[40:41], s98, v10, v[6:7]
	v_mad_u64_u32 v[190:191], s[40:41], s98, v4, v[8:9]
	v_mov_b32_e32 v10, v189
	v_mov_b32_e32 v4, v191
	v_mad_u64_u32 v[10:11], s[40:41], s98, v11, v[10:11]
	v_mad_u64_u32 v[4:5], s[40:41], s98, v5, v[4:5]
	s_mov_b64 s[40:41], 0x100
	v_mov_b32_e32 v191, v4
	v_lshl_add_u64 v[4:5], v[2:3], 0, s[40:41]
	v_mov_b32_e32 v189, v10
	v_lshl_add_u64 v[10:11], v[4:5], 0, s[36:37]
	v_lshl_add_u64 v[4:5], v[4:5], 0, s[38:39]
	v_mad_u64_u32 v[192:193], s[40:41], s98, v10, v[6:7]
	v_mad_u64_u32 v[194:195], s[40:41], s98, v4, v[8:9]
	v_mov_b32_e32 v10, v193
	v_mov_b32_e32 v4, v195
	v_mad_u64_u32 v[10:11], s[40:41], s98, v11, v[10:11]
	v_mad_u64_u32 v[4:5], s[40:41], s98, v5, v[4:5]
	s_mov_b64 s[40:41], 0x180
	s_nop 0
	v_lshl_add_u64 v[2:3], v[2:3], 0, s[40:41]
	v_mov_b32_e32 v195, v4
	v_lshl_add_u64 v[4:5], v[2:3], 0, s[36:37]
	v_lshl_add_u64 v[2:3], v[2:3], 0, s[38:39]
	v_mad_u64_u32 v[198:199], s[36:37], s98, v2, v[8:9]
	v_mad_u64_u32 v[196:197], s[36:37], s98, v4, v[6:7]
	v_mov_b32_e32 v2, v199
	s_waitcnt vmcnt(0)
; template <bool SWAP>
; DI void gemm_mainloop(f32x16 (&acc)[4][2], const u16* __restrict__ A, int lda, int rlo, int rhi,
;                       const u16* __restrict__ B, int ldb, int K, char* lds, const u16* zero_line) {
;     ...
; #pragma unroll
;   for (int mi = 0; mi < 4; ++mi)
; #pragma unroll
;     for (int ni = 0; ni < 2; ++ni)
; #pragma unroll
;       for (int i = 0; i < 16; ++i) acc[mi][ni][i] = 0.f;
;   const int gch = (lc ^ ((lr >> 1) & 7)) * 8;
;   const u16* ap = A + (ptrdiff_t)lr * lda + gch;
;   const u16* bp = B + (ptrdiff_t)lr * ldb + gch;
;   const int nk = K >> 6;
;   typedef __attribute__((address_space(3))) unsigned lds_u32;
;   auto glds = [&](int kt, int st) {
;     char* as_ = lds + st * 65536 + tid * 16;
; #pragma unroll
;     for (int i = 0; i < 4; ++i) {
;       const int rr = lr + 64 * i;
;       const u16* srca = (rr >= rlo && rr < rhi) ? (ap + (ptrdiff_t)(64 * i) * lda + kt * 64) : (zero_line + lc * 8);
;       __builtin_amdgcn_global_load_lds((const unsigned*)srca, (lds_u32*)(as_ + i * 8192), 16, 0, 0);
;       __builtin_amdgcn_global_load_lds((const unsigned*)(bp + (ptrdiff_t)(64 * i) * ldb + kt * 64), (lds_u32*)(as_ + 32768 + i * 8192), 16, 0, 0);
;     }
;   };
;   const int sw = (r >> 1) & 7;
;   const int arow_off = (wm * 128 + r) * 128;
;   const int brow_off = 32768 + (wn * 64 + r) * 128;
;   __syncthreads();
;   glds(0, 0);
;   asm volatile("s_waitcnt vmcnt(0)" ::: "memory");
;   __syncthreads();
	v_mov_b32_e32 v4, v197
	v_mad_u64_u32 v[2:3], s[36:37], s98, v3, v[2:3]
	v_mad_u64_u32 v[4:5], s[36:37], s98, v5, v[4:5]
	v_mov_b32_e32 v199, v2
	v_mov_b32_e32 v130, 0
	v_mov_b32_e32 v2, 0
	v_lshlrev_b32_e32 v0, 4, v0
	v_mov_b32_e32 v193, v10
	v_mov_b32_e32 v197, v4
	s_mov_b32 s25, 0x10000
	v_mov_b32_e32 v3, v2
	v_mov_b32_e32 v4, v2
	v_mov_b32_e32 v5, v2
	v_mov_b32_e32 v6, v2
	v_mov_b32_e32 v7, v2
	v_mov_b32_e32 v8, v2
	v_mov_b32_e32 v9, v2
	v_mov_b32_e32 v10, v2
	v_mov_b32_e32 v11, v2
	v_mov_b32_e32 v12, v2
	v_mov_b32_e32 v13, v2
	v_mov_b32_e32 v14, v2
	v_mov_b32_e32 v15, v2
	v_mov_b32_e32 v16, v2
	v_mov_b32_e32 v17, v2
	v_mov_b32_e32 v18, v2
	v_mov_b32_e32 v19, v2
	v_mov_b32_e32 v20, v2
	v_mov_b32_e32 v21, v2
	v_mov_b32_e32 v22, v2
	v_mov_b32_e32 v23, v2
	v_mov_b32_e32 v24, v2
	v_mov_b32_e32 v25, v2
	v_mov_b32_e32 v26, v2
	v_mov_b32_e32 v27, v2
	v_mov_b32_e32 v28, v2
	v_mov_b32_e32 v29, v2
	v_mov_b32_e32 v30, v2
	v_mov_b32_e32 v31, v2
	v_mov_b32_e32 v32, v2
	v_mov_b32_e32 v33, v2
	v_mov_b32_e32 v34, v2
	v_mov_b32_e32 v35, v2
	v_mov_b32_e32 v36, v2
	v_mov_b32_e32 v37, v2
	v_mov_b32_e32 v38, v2
	v_mov_b32_e32 v39, v2
	v_mov_b32_e32 v40, v2
	v_mov_b32_e32 v41, v2
	v_mov_b32_e32 v42, v2
	v_mov_b32_e32 v43, v2
	v_mov_b32_e32 v44, v2
	v_mov_b32_e32 v45, v2
	v_mov_b32_e32 v46, v2
	v_mov_b32_e32 v47, v2
	v_mov_b32_e32 v48, v2
	v_mov_b32_e32 v49, v2
	v_mov_b32_e32 v50, v2
	v_mov_b32_e32 v51, v2
	v_mov_b32_e32 v52, v2
	v_mov_b32_e32 v53, v2
	v_mov_b32_e32 v54, v2
	v_mov_b32_e32 v55, v2
	v_mov_b32_e32 v56, v2
	v_mov_b32_e32 v57, v2
	v_mov_b32_e32 v58, v2
	v_mov_b32_e32 v59, v2
	v_mov_b32_e32 v60, v2
	v_mov_b32_e32 v61, v2
	v_mov_b32_e32 v62, v2
	v_mov_b32_e32 v63, v2
	v_mov_b32_e32 v64, v2
	v_mov_b32_e32 v65, v2
	v_mov_b32_e32 v66, v2
	v_mov_b32_e32 v67, v2
	v_mov_b32_e32 v68, v2
	v_mov_b32_e32 v69, v2
	v_mov_b32_e32 v70, v2
	v_mov_b32_e32 v71, v2
	v_mov_b32_e32 v72, v2
	v_mov_b32_e32 v73, v2
	v_mov_b32_e32 v74, v2
	v_mov_b32_e32 v75, v2
	v_mov_b32_e32 v76, v2
	v_mov_b32_e32 v77, v2
	v_mov_b32_e32 v78, v2
	v_mov_b32_e32 v79, v2
	v_mov_b32_e32 v80, v2
	v_mov_b32_e32 v81, v2
	v_mov_b32_e32 v82, v2
	v_mov_b32_e32 v83, v2
	v_mov_b32_e32 v84, v2
	v_mov_b32_e32 v85, v2
	v_mov_b32_e32 v86, v2
	v_mov_b32_e32 v87, v2
	v_mov_b32_e32 v88, v2
	v_mov_b32_e32 v89, v2
	v_mov_b32_e32 v90, v2
	v_mov_b32_e32 v91, v2
	v_mov_b32_e32 v92, v2
	v_mov_b32_e32 v93, v2
	v_mov_b32_e32 v94, v2
	v_mov_b32_e32 v95, v2
	v_mov_b32_e32 v96, v2
	v_mov_b32_e32 v97, v2
	v_mov_b32_e32 v98, v2
	v_mov_b32_e32 v99, v2
	v_mov_b32_e32 v100, v2
	v_mov_b32_e32 v101, v2
	v_mov_b32_e32 v102, v2
	v_mov_b32_e32 v103, v2
	v_mov_b32_e32 v104, v2
	v_mov_b32_e32 v105, v2
	v_mov_b32_e32 v106, v2
	v_mov_b32_e32 v107, v2
	v_mov_b32_e32 v108, v2
	v_mov_b32_e32 v109, v2
	v_mov_b32_e32 v110, v2
	v_mov_b32_e32 v111, v2
	v_mov_b32_e32 v112, v2
	v_mov_b32_e32 v113, v2
	v_mov_b32_e32 v114, v2
	v_mov_b32_e32 v115, v2
	v_mov_b32_e32 v116, v2
	v_mov_b32_e32 v117, v2
	v_mov_b32_e32 v118, v2
	v_mov_b32_e32 v119, v2
	v_mov_b32_e32 v120, v2
	v_mov_b32_e32 v121, v2
	v_mov_b32_e32 v122, v2
	v_mov_b32_e32 v123, v2
	v_mov_b32_e32 v124, v2
	v_mov_b32_e32 v125, v2
	v_mov_b32_e32 v126, v2
	v_mov_b32_e32 v127, v2
	v_mov_b32_e32 v128, v2
	v_mov_b32_e32 v129, v2
	v_mov_b32_e32 v131, v130
	v_mov_b32_e32 v132, v130
	v_mov_b32_e32 v133, v130
	v_mov_b32_e32 v134, v130
	v_mov_b32_e32 v135, v130
	v_mov_b32_e32 v136, v130
	v_mov_b32_e32 v137, v130
	v_mov_b32_e32 v142, v130
	v_mov_b32_e32 v143, v130
	v_mov_b32_e32 v144, v130
	v_mov_b32_e32 v145, v130
	v_mov_b32_e32 v150, v130
	v_mov_b32_e32 v151, v130
	v_mov_b32_e32 v152, v130
	v_mov_b32_e32 v153, v130
	v_mov_b32_e32 v138, v130
	v_mov_b32_e32 v139, v130
	v_mov_b32_e32 v140, v130
	v_mov_b32_e32 v141, v130
	v_mov_b32_e32 v146, v130
	v_mov_b32_e32 v147, v130
	v_mov_b32_e32 v148, v130
	v_mov_b32_e32 v149, v130
	s_waitcnt vmcnt(0) lgkmcnt(0)
	s_barrier
	v_mov_b32_e32 v246, v178
	v_mov_b32_e32 v247, v179
	v_mov_b32_e32 v248, v200
	s_mul_i32 s6, s24, s98
	s_mul_hi_u32 s7, s24, s98
	s_lshl_b64 s[6:7], s[6:7], 1
	s_add_u32 s6, s16, s6
	s_addc_u32 s7, s17, s7
	s_mul_i32 s8, s34, s98
	s_mul_hi_u32 s9, s34, s98
	s_lshl_b64 s[8:9], s[8:9], 1
	s_add_u32 s8, s12, s8
	s_addc_u32 s9, s13, s9
	s_lshl_b32 s10, s98, 7
	s_mov_b32 s11, 0
	s_lshr_b32 s28, s98, 6
	s_add_i32 s28, s28, -2
	v_and_b32_e32 v130, 63, v204
	v_lshrrev_b32_e32 v131, 6, v204
	v_lshrrev_b32_e32 v132, 3, v204
	v_lshrrev_b32_e32 v0, 4, v130
	v_lshl_add_u32 v0, v131, 2, v0
	v_xor_b32_e32 v0, v0, v130
	v_and_b32_e32 v0, 7, v0
	v_lshlrev_b32_e32 v133, 4, v0
	v_mul_lo_u32 v0, v132, s98
	v_lshl_add_u32 v0, v0, 1, v133
	v_lshl_add_u64 v[182:183], s[8:9], 0, v[0:1]
	v_lshl_add_u64 v[200:201], v[182:183], 0, s[10:11]
	v_lshl_add_u64 v[198:199], v[200:201], 0, s[10:11]
	v_lshl_add_u64 v[202:203], v[198:199], 0, s[10:11]
	v_and_b32_e32 v0, 31, v132
	v_lshrrev_b32_e32 v130, 5, v132
	v_lshl_add_u32 v0, v130, 6, v0
	v_mul_lo_u32 v0, v0, s98
	v_lshl_add_u32 v0, v0, 1, v133
	s_lshl_b32 s10, s98, 6
	v_lshl_add_u64 v[228:229], s[6:7], 0, v[0:1]
	v_lshl_add_u64 v[232:233], v[228:229], 0, s[10:11]
	s_lshl_b32 s10, s98, 8
	v_lshl_add_u64 v[230:231], v[228:229], 0, s[10:11]
	v_lshl_add_u64 v[234:235], v[232:233], 0, s[10:11]
	v_and_b32_e32 v132, 31, v204
	v_lshrrev_b32_e32 v0, 2, v131
	v_lshl_add_u32 v0, v0, 6, v132
	v_lshlrev_b32_e32 v240, 7, v0
	v_and_b32_e32 v0, 3, v131
	v_lshl_add_u32 v0, v0, 5, v132
	v_lshlrev_b32_e32 v241, 7, v0
	v_bfe_u32 v0, v204, 5, 1
	v_bfe_u32 v130, v132, 1, 3
	v_or_b32_e32 v133, 0, v0
	v_xor_b32_e32 v133, v133, v130
	v_lshlrev_b32_e32 v236, 4, v133
	v_or_b32_e32 v133, 2, v0
	v_xor_b32_e32 v133, v133, v130
	v_lshlrev_b32_e32 v237, 4, v133
	v_or_b32_e32 v133, 4, v0
	v_xor_b32_e32 v133, v133, v130
	v_lshlrev_b32_e32 v238, 4, v133
	v_or_b32_e32 v133, 6, v0
	v_xor_b32_e32 v133, v133, v130
	v_lshlrev_b32_e32 v239, 4, v133
	v_lshlrev_b32_e32 v131, 10, v131
	s_nop 0
	v_readfirstlane_b32 s100, v131
	s_mov_b32 s25, 0
	s_add_u32 m0, s100, 0x8000
	s_nop 0
	global_load_lds_dwordx4 v[228:229], off
	s_add_u32 m0, s100, 0xa000
	v_lshl_add_u64 v[228:229], v[228:229], 0, s[4:5]
	global_load_lds_dwordx4 v[230:231], off
	v_lshl_add_u64 v[230:231], v[230:231], 0, s[4:5]
	s_add_u32 m0, s100, 0x0
	s_nop 0
	global_load_lds_dwordx4 v[182:183], off
	s_add_u32 m0, s100, 0x2000
	v_lshl_add_u64 v[182:183], v[182:183], 0, s[4:5]
	global_load_lds_dwordx4 v[198:199], off
	v_lshl_add_u64 v[198:199], v[198:199], 0, s[4:5]
	s_add_u32 m0, s100, 0xc000
	s_nop 0
	global_load_lds_dwordx4 v[232:233], off
	s_add_u32 m0, s100, 0xe000
	v_lshl_add_u64 v[232:233], v[232:233], 0, s[4:5]
	global_load_lds_dwordx4 v[234:235], off
	v_lshl_add_u64 v[234:235], v[234:235], 0, s[4:5]
	s_add_u32 m0, s100, 0x4000
	s_nop 0
	global_load_lds_dwordx4 v[200:201], off
	s_add_u32 m0, s100, 0x6000
	v_lshl_add_u64 v[200:201], v[200:201], 0, s[4:5]
	global_load_lds_dwordx4 v[202:203], off
	v_lshl_add_u64 v[202:203], v[202:203], 0, s[4:5]
	s_cmp_eq_u32 s101, 1
	s_cbranch_scc0 .Lg8_m246_p0
	s_barrier
; #define MFMA(a, b, c) __builtin_amdgcn_mfma_f32_32x32x16_bf16((a), (b), (c), 0, 0, 0)
; template <bool SWAP>
; DI void gemm_mainloop(f32x16 (&acc)[4][2], const u16* __restrict__ A, int lda, int rlo, int rhi,
;                       const u16* __restrict__ B, int ldb, int K, char* lds, const u16* zero_line) {
;     ...
;   auto ldfrag = [&](const char* st, int ks, int buf) {
;     const int co = ((2 * ks + h) ^ sw) << 4;
; #pragma unroll
;     for (int mi = 0; mi < 4; ++mi) fa[buf][mi] = *(const bf16x8*)(st + arow_off + mi * 4096 + co);
; #pragma unroll
;     for (int ni = 0; ni < 2; ++ni) fb[buf][ni] = *(const bf16x8*)(st + brow_off + ni * 4096 + co);
;   };
;   auto mma = [&](int buf) {
; #pragma unroll
;     for (int mi = 0; mi < 4; ++mi)
; #pragma unroll
;       for (int ni = 0; ni < 2; ++ni)
;         acc[mi][ni] = SWAP ? MFMA(fb[buf][ni], fa[buf][mi], acc[mi][ni]) : MFMA(fa[buf][mi], fb[buf][ni], acc[mi][ni]);
;   };
;   auto pat_rd = [&]() {
; #pragma unroll
;     for (int g = 0; g < 6; ++g) {
;       __builtin_amdgcn_sched_group_barrier(0x100, 1, 0);
;       __builtin_amdgcn_sched_group_barrier(0x008, 1, 0);
;     }
;     __builtin_amdgcn_sched_group_barrier(0x008, 2, 0);
;   };
; #pragma unroll 2
;   for (int kt = 0; kt < nk; ++kt) {
;     const char* st = lds + (kt & 1) * 65536;
;     ldfrag(st, 0, 0);
;     mma(1);
;     pat_rd();
;     if (kt + 1 < nk) glds(kt + 1, (kt + 1) & 1);
;     ldfrag(st, 1, 1);
;     mma(0);
;     pat_rd();
;     ldfrag(st, 2, 0);
;     mma(1);
;     pat_rd();
;     ldfrag(st, 3, 1);
;     mma(0);
;     pat_rd();
;     asm volatile("s_waitcnt vmcnt(0)" ::: "memory");
;     __syncthreads();
.Lg8_m246_p0:
	s_waitcnt vmcnt(4)
	s_barrier
	s_add_u32 m0, s100, 0x18000
	s_nop 0
	global_load_lds_dwordx4 v[228:229], off
	s_add_u32 m0, s100, 0x1a000
	v_lshl_add_u64 v[228:229], v[228:229], 0, s[4:5]
	global_load_lds_dwordx4 v[230:231], off
	v_lshl_add_u64 v[230:231], v[230:231], 0, s[4:5]
	s_add_u32 m0, s100, 0x10000
	s_nop 0
	global_load_lds_dwordx4 v[182:183], off
	s_add_u32 m0, s100, 0x12000
	v_lshl_add_u64 v[182:183], v[182:183], 0, s[4:5]
	global_load_lds_dwordx4 v[198:199], off
	v_lshl_add_u64 v[198:199], v[198:199], 0, s[4:5]
	s_add_u32 m0, s100, 0x1c000
	s_nop 0
	global_load_lds_dwordx4 v[232:233], off
	s_add_u32 m0, s100, 0x1e000
	v_lshl_add_u64 v[232:233], v[232:233], 0, s[4:5]
	global_load_lds_dwordx4 v[234:235], off
	v_lshl_add_u64 v[234:235], v[234:235], 0, s[4:5]
	s_waitcnt vmcnt(6)
	s_barrier
	s_mov_b32 s36, 0x10000
.Lg8_m246:
	v_add3_u32 v242, v241, v236, 0
	v_add3_u32 v243, v241, v237, 0
	v_add3_u32 v244, v241, v238, 0
	v_add3_u32 v245, v241, v239, 0
	ds_read_b128 v[162:165], v242 offset:32768
	ds_read_b128 v[166:169], v243 offset:32768
	ds_read_b128 v[170:173], v244 offset:32768
	ds_read_b128 v[174:177], v245 offset:32768
	v_add3_u32 v242, v240, v236, 0
	v_add3_u32 v243, v240, v237, 0
	v_add3_u32 v244, v240, v238, 0
	v_add3_u32 v245, v240, v239, 0
	ds_read_b128 v[130:133], v242
	ds_read_b128 v[134:137], v243
	ds_read_b128 v[138:141], v244
	ds_read_b128 v[142:145], v245
	ds_read_b128 v[146:149], v242 offset:4096
	ds_read_b128 v[150:153], v243 offset:4096
	ds_read_b128 v[154:157], v244 offset:4096
	ds_read_b128 v[158:161], v245 offset:4096
	s_add_u32 m0, s100, 0x14000
	s_nop 0
	global_load_lds_dwordx4 v[200:201], off
	s_add_u32 m0, s100, 0x16000
	v_lshl_add_u64 v[200:201], v[200:201], 0, s[4:5]
	global_load_lds_dwordx4 v[202:203], off
	v_lshl_add_u64 v[202:203], v[202:203], 0, s[4:5]
	s_waitcnt lgkmcnt(8)
	s_barrier
	s_waitcnt lgkmcnt(0)
	v_mfma_f32_32x32x16_bf16 v[114:129], v[162:165], v[130:133], v[114:129]
	v_mfma_f32_32x32x16_bf16 v[82:97], v[162:165], v[146:149], v[82:97]
	v_mfma_f32_32x32x16_bf16 v[114:129], v[166:169], v[134:137], v[114:129]
	v_mfma_f32_32x32x16_bf16 v[82:97], v[166:169], v[150:153], v[82:97]
	v_mfma_f32_32x32x16_bf16 v[114:129], v[170:173], v[138:141], v[114:129]
	v_mfma_f32_32x32x16_bf16 v[82:97], v[170:173], v[154:157], v[82:97]
	v_mfma_f32_32x32x16_bf16 v[114:129], v[174:177], v[142:145], v[114:129]
	v_mfma_f32_32x32x16_bf16 v[82:97], v[174:177], v[158:161], v[82:97]
	s_barrier
	v_add3_u32 v242, v241, v236, 0
	v_add3_u32 v243, v241, v237, 0
	v_add3_u32 v244, v241, v238, 0
	v_add3_u32 v245, v241, v239, 0
	ds_read_b128 v[178:181], v242 offset:49152
	ds_read_b128 v[186:189], v243 offset:49152
	ds_read_b128 v[190:193], v244 offset:49152
	ds_read_b128 v[194:197], v245 offset:49152
	s_add_u32 m0, s100, 0x8000
	s_nop 0
	global_load_lds_dwordx4 v[228:229], off
	s_add_u32 m0, s100, 0xa000
	v_lshl_add_u64 v[228:229], v[228:229], 0, s[4:5]
	global_load_lds_dwordx4 v[230:231], off
	v_lshl_add_u64 v[230:231], v[230:231], 0, s[4:5]
	s_barrier
	s_waitcnt lgkmcnt(0)
	v_mfma_f32_32x32x16_bf16 v[98:113], v[178:181], v[130:133], v[98:113]
	v_mfma_f32_32x32x16_bf16 v[66:81], v[178:181], v[146:149], v[66:81]
	v_mfma_f32_32x32x16_bf16 v[98:113], v[186:189], v[134:137], v[98:113]
	v_mfma_f32_32x32x16_bf16 v[66:81], v[186:189], v[150:153], v[66:81]
	v_mfma_f32_32x32x16_bf16 v[98:113], v[190:193], v[138:141], v[98:113]
	v_mfma_f32_32x32x16_bf16 v[66:81], v[190:193], v[154:157], v[66:81]
	v_mfma_f32_32x32x16_bf16 v[98:113], v[194:197], v[142:145], v[98:113]
	v_mfma_f32_32x32x16_bf16 v[66:81], v[194:197], v[158:161], v[66:81]
	s_barrier
	v_add3_u32 v242, v240, v236, 0
	v_add3_u32 v243, v240, v237, 0
	v_add3_u32 v244, v240, v238, 0
	v_add3_u32 v245, v240, v239, 0
	ds_read_b128 v[130:133], v242 offset:16384
	ds_read_b128 v[134:137], v243 offset:16384
	ds_read_b128 v[138:141], v244 offset:16384
	ds_read_b128 v[142:145], v245 offset:16384
	ds_read_b128 v[146:149], v242 offset:20480
	ds_read_b128 v[150:153], v243 offset:20480
	ds_read_b128 v[154:157], v244 offset:20480
	ds_read_b128 v[158:161], v245 offset:20480
	s_add_u32 m0, s100, 0x0
	s_nop 0
	global_load_lds_dwordx4 v[182:183], off
	s_add_u32 m0, s100, 0x2000
	v_lshl_add_u64 v[182:183], v[182:183], 0, s[4:5]
	global_load_lds_dwordx4 v[198:199], off
	v_lshl_add_u64 v[198:199], v[198:199], 0, s[4:5]
	s_barrier
	s_waitcnt lgkmcnt(0)
	v_mfma_f32_32x32x16_bf16 v[50:65], v[162:165], v[130:133], v[50:65]
	v_mfma_f32_32x32x16_bf16 v[18:33], v[162:165], v[146:149], v[18:33]
	v_mfma_f32_32x32x16_bf16 v[50:65], v[166:169], v[134:137], v[50:65]
	v_mfma_f32_32x32x16_bf16 v[18:33], v[166:169], v[150:153], v[18:33]
	v_mfma_f32_32x32x16_bf16 v[50:65], v[170:173], v[138:141], v[50:65]
	v_mfma_f32_32x32x16_bf16 v[18:33], v[170:173], v[154:157], v[18:33]
	v_mfma_f32_32x32x16_bf16 v[50:65], v[174:177], v[142:145], v[50:65]
	v_mfma_f32_32x32x16_bf16 v[18:33], v[174:177], v[158:161], v[18:33]
	s_barrier
	s_add_u32 m0, s100, 0xc000
	s_nop 0
	global_load_lds_dwordx4 v[232:233], off
	s_add_u32 m0, s100, 0xe000
	v_lshl_add_u64 v[232:233], v[232:233], 0, s[4:5]
	global_load_lds_dwordx4 v[234:235], off
	v_lshl_add_u64 v[234:235], v[234:235], 0, s[4:5]
	s_waitcnt vmcnt(6)
	s_barrier
	v_mfma_f32_32x32x16_bf16 v[34:49], v[178:181], v[130:133], v[34:49]
	v_mfma_f32_32x32x16_bf16 v[2:17], v[178:181], v[146:149], v[2:17]
	v_mfma_f32_32x32x16_bf16 v[34:49], v[186:189], v[134:137], v[34:49]
	v_mfma_f32_32x32x16_bf16 v[2:17], v[186:189], v[150:153], v[2:17]
	v_mfma_f32_32x32x16_bf16 v[34:49], v[190:193], v[138:141], v[34:49]
	v_mfma_f32_32x32x16_bf16 v[2:17], v[190:193], v[154:157], v[2:17]
	v_mfma_f32_32x32x16_bf16 v[34:49], v[194:197], v[142:145], v[34:49]
	v_mfma_f32_32x32x16_bf16 v[2:17], v[194:197], v[158:161], v[2:17]
	s_barrier
; #define MFMA(a, b, c) __builtin_amdgcn_mfma_f32_32x32x16_bf16((a), (b), (c), 0, 0, 0)
; template <bool SWAP>
; DI void gemm_mainloop(f32x16 (&acc)[4][2], const u16* __restrict__ A, int lda, int rlo, int rhi,
;                       const u16* __restrict__ B, int ldb, int K, char* lds, const u16* zero_line) {
;     ...
;   auto ldfrag = [&](const char* st, int ks, int buf) {
;     const int co = ((2 * ks + h) ^ sw) << 4;
; #pragma unroll
;     for (int mi = 0; mi < 4; ++mi) fa[buf][mi] = *(const bf16x8*)(st + arow_off + mi * 4096 + co);
; #pragma unroll
;     for (int ni = 0; ni < 2; ++ni) fb[buf][ni] = *(const bf16x8*)(st + brow_off + ni * 4096 + co);
;   };
;   auto mma = [&](int buf) {
; #pragma unroll
;     for (int mi = 0; mi < 4; ++mi)
; #pragma unroll
;       for (int ni = 0; ni < 2; ++ni)
;         acc[mi][ni] = SWAP ? MFMA(fb[buf][ni], fa[buf][mi], acc[mi][ni]) : MFMA(fa[buf][mi], fb[buf][ni], acc[mi][ni]);
;   };
;   auto pat_rd = [&]() {
; #pragma unroll
;     for (int g = 0; g < 6; ++g) {
;       __builtin_amdgcn_sched_group_barrier(0x100, 1, 0);
;       __builtin_amdgcn_sched_group_barrier(0x008, 1, 0);
;     }
;     __builtin_amdgcn_sched_group_barrier(0x008, 2, 0);
;   };
; #pragma unroll 2
;   for (int kt = 0; kt < nk; ++kt) {
;     const char* st = lds + (kt & 1) * 65536;
;     ldfrag(st, 0, 0);
;     mma(1);
;     pat_rd();
;     if (kt + 1 < nk) glds(kt + 1, (kt + 1) & 1);
;     ldfrag(st, 1, 1);
;     mma(0);
;     pat_rd();
;     ldfrag(st, 2, 0);
;     mma(1);
;     pat_rd();
;     ldfrag(st, 3, 1);
;     mma(0);
;     pat_rd();
;     asm volatile("s_waitcnt vmcnt(0)" ::: "memory");
;     __syncthreads();
	v_add3_u32 v242, v241, v236, s36
	v_add3_u32 v243, v241, v237, s36
	v_add3_u32 v244, v241, v238, s36
	v_add3_u32 v245, v241, v239, s36
	ds_read_b128 v[162:165], v242 offset:32768
	ds_read_b128 v[166:169], v243 offset:32768
	ds_read_b128 v[170:173], v244 offset:32768
	ds_read_b128 v[174:177], v245 offset:32768
	v_add3_u32 v242, v240, v236, s36
	v_add3_u32 v243, v240, v237, s36
	v_add3_u32 v244, v240, v238, s36
	v_add3_u32 v245, v240, v239, s36
	ds_read_b128 v[130:133], v242
	ds_read_b128 v[134:137], v243
	ds_read_b128 v[138:141], v244
	ds_read_b128 v[142:145], v245
	ds_read_b128 v[146:149], v242 offset:4096
	ds_read_b128 v[150:153], v243 offset:4096
	ds_read_b128 v[154:157], v244 offset:4096
	ds_read_b128 v[158:161], v245 offset:4096
	s_add_u32 m0, s100, 0x4000
	s_nop 0
	global_load_lds_dwordx4 v[200:201], off
	s_add_u32 m0, s100, 0x6000
	v_lshl_add_u64 v[200:201], v[200:201], 0, s[4:5]
	global_load_lds_dwordx4 v[202:203], off
	v_lshl_add_u64 v[202:203], v[202:203], 0, s[4:5]
	s_waitcnt lgkmcnt(8)
	s_barrier
	s_waitcnt lgkmcnt(0)
	v_mfma_f32_32x32x16_bf16 v[114:129], v[162:165], v[130:133], v[114:129]
	v_mfma_f32_32x32x16_bf16 v[82:97], v[162:165], v[146:149], v[82:97]
	v_mfma_f32_32x32x16_bf16 v[114:129], v[166:169], v[134:137], v[114:129]
	v_mfma_f32_32x32x16_bf16 v[82:97], v[166:169], v[150:153], v[82:97]
	v_mfma_f32_32x32x16_bf16 v[114:129], v[170:173], v[138:141], v[114:129]
	v_mfma_f32_32x32x16_bf16 v[82:97], v[170:173], v[154:157], v[82:97]
	v_mfma_f32_32x32x16_bf16 v[114:129], v[174:177], v[142:145], v[114:129]
	v_mfma_f32_32x32x16_bf16 v[82:97], v[174:177], v[158:161], v[82:97]
	s_barrier
	v_add3_u32 v242, v241, v236, s36
	v_add3_u32 v243, v241, v237, s36
	v_add3_u32 v244, v241, v238, s36
	v_add3_u32 v245, v241, v239, s36
	ds_read_b128 v[178:181], v242 offset:49152
	ds_read_b128 v[186:189], v243 offset:49152
	ds_read_b128 v[190:193], v244 offset:49152
	ds_read_b128 v[194:197], v245 offset:49152
	s_add_u32 m0, s100, 0x18000
	s_nop 0
	global_load_lds_dwordx4 v[228:229], off
	s_add_u32 m0, s100, 0x1a000
	v_lshl_add_u64 v[228:229], v[228:229], 0, s[4:5]
	global_load_lds_dwordx4 v[230:231], off
	v_lshl_add_u64 v[230:231], v[230:231], 0, s[4:5]
	s_barrier
	s_waitcnt lgkmcnt(0)
	v_mfma_f32_32x32x16_bf16 v[98:113], v[178:181], v[130:133], v[98:113]
	v_mfma_f32_32x32x16_bf16 v[66:81], v[178:181], v[146:149], v[66:81]
	v_mfma_f32_32x32x16_bf16 v[98:113], v[186:189], v[134:137], v[98:113]
	v_mfma_f32_32x32x16_bf16 v[66:81], v[186:189], v[150:153], v[66:81]
	v_mfma_f32_32x32x16_bf16 v[98:113], v[190:193], v[138:141], v[98:113]
	v_mfma_f32_32x32x16_bf16 v[66:81], v[190:193], v[154:157], v[66:81]
	v_mfma_f32_32x32x16_bf16 v[98:113], v[194:197], v[142:145], v[98:113]
	v_mfma_f32_32x32x16_bf16 v[66:81], v[194:197], v[158:161], v[66:81]
	s_barrier
	v_add3_u32 v242, v240, v236, s36
	v_add3_u32 v243, v240, v237, s36
	v_add3_u32 v244, v240, v238, s36
	v_add3_u32 v245, v240, v239, s36
	ds_read_b128 v[130:133], v242 offset:16384
	ds_read_b128 v[134:137], v243 offset:16384
	ds_read_b128 v[138:141], v244 offset:16384
	ds_read_b128 v[142:145], v245 offset:16384
	ds_read_b128 v[146:149], v242 offset:20480
	ds_read_b128 v[150:153], v243 offset:20480
	ds_read_b128 v[154:157], v244 offset:20480
	ds_read_b128 v[158:161], v245 offset:20480
	s_add_u32 m0, s100, 0x10000
	s_nop 0
	global_load_lds_dwordx4 v[182:183], off
	s_add_u32 m0, s100, 0x12000
	v_lshl_add_u64 v[182:183], v[182:183], 0, s[4:5]
	global_load_lds_dwordx4 v[198:199], off
	v_lshl_add_u64 v[198:199], v[198:199], 0, s[4:5]
	s_barrier
	s_waitcnt lgkmcnt(0)
	v_mfma_f32_32x32x16_bf16 v[50:65], v[162:165], v[130:133], v[50:65]
	v_mfma_f32_32x32x16_bf16 v[18:33], v[162:165], v[146:149], v[18:33]
	v_mfma_f32_32x32x16_bf16 v[50:65], v[166:169], v[134:137], v[50:65]
	v_mfma_f32_32x32x16_bf16 v[18:33], v[166:169], v[150:153], v[18:33]
	v_mfma_f32_32x32x16_bf16 v[50:65], v[170:173], v[138:141], v[50:65]
	v_mfma_f32_32x32x16_bf16 v[18:33], v[170:173], v[154:157], v[18:33]
	v_mfma_f32_32x32x16_bf16 v[50:65], v[174:177], v[142:145], v[50:65]
	v_mfma_f32_32x32x16_bf16 v[18:33], v[174:177], v[158:161], v[18:33]
	s_barrier
	s_add_u32 m0, s100, 0x1c000
	s_nop 0
	global_load_lds_dwordx4 v[232:233], off
	s_add_u32 m0, s100, 0x1e000
	v_lshl_add_u64 v[232:233], v[232:233], 0, s[4:5]
	global_load_lds_dwordx4 v[234:235], off
	v_lshl_add_u64 v[234:235], v[234:235], 0, s[4:5]
	s_waitcnt vmcnt(6)
	s_barrier
	v_mfma_f32_32x32x16_bf16 v[34:49], v[178:181], v[130:133], v[34:49]
	v_mfma_f32_32x32x16_bf16 v[2:17], v[178:181], v[146:149], v[2:17]
	v_mfma_f32_32x32x16_bf16 v[34:49], v[186:189], v[134:137], v[34:49]
	v_mfma_f32_32x32x16_bf16 v[2:17], v[186:189], v[150:153], v[2:17]
	v_mfma_f32_32x32x16_bf16 v[34:49], v[190:193], v[138:141], v[34:49]
	v_mfma_f32_32x32x16_bf16 v[2:17], v[190:193], v[154:157], v[2:17]
	v_mfma_f32_32x32x16_bf16 v[34:49], v[194:197], v[142:145], v[34:49]
	v_mfma_f32_32x32x16_bf16 v[2:17], v[194:197], v[158:161], v[2:17]
	s_barrier
	s_add_i32 s25, s25, 2
	s_cmp_lt_u32 s25, s28
	s_cbranch_scc1 .Lg8_m246
	v_add3_u32 v242, v241, v236, 0
	v_add3_u32 v243, v241, v237, 0
	v_add3_u32 v244, v241, v238, 0
	v_add3_u32 v245, v241, v239, 0
	ds_read_b128 v[162:165], v242 offset:32768
	ds_read_b128 v[166:169], v243 offset:32768
	ds_read_b128 v[170:173], v244 offset:32768
	ds_read_b128 v[174:177], v245 offset:32768
	v_add3_u32 v242, v240, v236, 0
	v_add3_u32 v243, v240, v237, 0
	v_add3_u32 v244, v240, v238, 0
	v_add3_u32 v245, v240, v239, 0
	ds_read_b128 v[130:133], v242
	ds_read_b128 v[134:137], v243
	ds_read_b128 v[138:141], v244
	ds_read_b128 v[142:145], v245
	ds_read_b128 v[146:149], v242 offset:4096
	ds_read_b128 v[150:153], v243 offset:4096
	ds_read_b128 v[154:157], v244 offset:4096
	ds_read_b128 v[158:161], v245 offset:4096
	s_add_u32 m0, s100, 0x14000
	s_nop 0
	global_load_lds_dwordx4 v[200:201], off
	s_add_u32 m0, s100, 0x16000
	v_lshl_add_u64 v[200:201], v[200:201], 0, s[4:5]
	global_load_lds_dwordx4 v[202:203], off
	v_lshl_add_u64 v[202:203], v[202:203], 0, s[4:5]
	s_barrier
; #define MFMA(a, b, c) __builtin_amdgcn_mfma_f32_32x32x16_bf16((a), (b), (c), 0, 0, 0)
; template <bool SWAP>
; DI void gemm_mainloop(f32x16 (&acc)[4][2], const u16* __restrict__ A, int lda, int rlo, int rhi,
;                       const u16* __restrict__ B, int ldb, int K, char* lds, const u16* zero_line) {
;     ...
;   auto ldfrag = [&](const char* st, int ks, int buf) {
;     const int co = ((2 * ks + h) ^ sw) << 4;
; #pragma unroll
;     for (int mi = 0; mi < 4; ++mi) fa[buf][mi] = *(const bf16x8*)(st + arow_off + mi * 4096 + co);
; #pragma unroll
;     for (int ni = 0; ni < 2; ++ni) fb[buf][ni] = *(const bf16x8*)(st + brow_off + ni * 4096 + co);
;   };
;   auto mma = [&](int buf) {
; #pragma unroll
;     for (int mi = 0; mi < 4; ++mi)
; #pragma unroll
;       for (int ni = 0; ni < 2; ++ni)
;         acc[mi][ni] = SWAP ? MFMA(fb[buf][ni], fa[buf][mi], acc[mi][ni]) : MFMA(fa[buf][mi], fb[buf][ni], acc[mi][ni]);
;   };
;   auto pat_rd = [&]() {
; #pragma unroll
;     for (int g = 0; g < 6; ++g) {
;       __builtin_amdgcn_sched_group_barrier(0x100, 1, 0);
;       __builtin_amdgcn_sched_group_barrier(0x008, 1, 0);
;     }
;     __builtin_amdgcn_sched_group_barrier(0x008, 2, 0);
;   };
; #pragma unroll 2
;   for (int kt = 0; kt < nk; ++kt) {
;     const char* st = lds + (kt & 1) * 65536;
;     ldfrag(st, 0, 0);
;     mma(1);
;     pat_rd();
;     if (kt + 1 < nk) glds(kt + 1, (kt + 1) & 1);
;     ldfrag(st, 1, 1);
;     mma(0);
;     pat_rd();
;     ldfrag(st, 2, 0);
;     mma(1);
;     pat_rd();
;     ldfrag(st, 3, 1);
;     mma(0);
;     pat_rd();
;     asm volatile("s_waitcnt vmcnt(0)" ::: "memory");
;     __syncthreads();
;   }
;   mma(1);
	s_waitcnt lgkmcnt(0)
	v_mfma_f32_32x32x16_bf16 v[114:129], v[162:165], v[130:133], v[114:129]
	v_mfma_f32_32x32x16_bf16 v[82:97], v[162:165], v[146:149], v[82:97]
	v_mfma_f32_32x32x16_bf16 v[114:129], v[166:169], v[134:137], v[114:129]
	v_mfma_f32_32x32x16_bf16 v[82:97], v[166:169], v[150:153], v[82:97]
	v_mfma_f32_32x32x16_bf16 v[114:129], v[170:173], v[138:141], v[114:129]
	v_mfma_f32_32x32x16_bf16 v[82:97], v[170:173], v[154:157], v[82:97]
	v_mfma_f32_32x32x16_bf16 v[114:129], v[174:177], v[142:145], v[114:129]
	v_mfma_f32_32x32x16_bf16 v[82:97], v[174:177], v[158:161], v[82:97]
	s_barrier
	v_add3_u32 v242, v241, v236, 0
	v_add3_u32 v243, v241, v237, 0
	v_add3_u32 v244, v241, v238, 0
	v_add3_u32 v245, v241, v239, 0
	ds_read_b128 v[178:181], v242 offset:49152
	ds_read_b128 v[186:189], v243 offset:49152
	ds_read_b128 v[190:193], v244 offset:49152
	ds_read_b128 v[194:197], v245 offset:49152
	s_barrier
	s_waitcnt lgkmcnt(0)
	v_mfma_f32_32x32x16_bf16 v[98:113], v[178:181], v[130:133], v[98:113]
	v_mfma_f32_32x32x16_bf16 v[66:81], v[178:181], v[146:149], v[66:81]
	v_mfma_f32_32x32x16_bf16 v[98:113], v[186:189], v[134:137], v[98:113]
	v_mfma_f32_32x32x16_bf16 v[66:81], v[186:189], v[150:153], v[66:81]
	v_mfma_f32_32x32x16_bf16 v[98:113], v[190:193], v[138:141], v[98:113]
	v_mfma_f32_32x32x16_bf16 v[66:81], v[190:193], v[154:157], v[66:81]
	v_mfma_f32_32x32x16_bf16 v[98:113], v[194:197], v[142:145], v[98:113]
	v_mfma_f32_32x32x16_bf16 v[66:81], v[194:197], v[158:161], v[66:81]
	s_barrier
	v_add3_u32 v242, v240, v236, 0
	v_add3_u32 v243, v240, v237, 0
	v_add3_u32 v244, v240, v238, 0
	v_add3_u32 v245, v240, v239, 0
	ds_read_b128 v[130:133], v242 offset:16384
	ds_read_b128 v[134:137], v243 offset:16384
	ds_read_b128 v[138:141], v244 offset:16384
	ds_read_b128 v[142:145], v245 offset:16384
	ds_read_b128 v[146:149], v242 offset:20480
	ds_read_b128 v[150:153], v243 offset:20480
	ds_read_b128 v[154:157], v244 offset:20480
	ds_read_b128 v[158:161], v245 offset:20480
	s_waitcnt vmcnt(4)
	s_barrier
	s_waitcnt lgkmcnt(0)
	v_mfma_f32_32x32x16_bf16 v[50:65], v[162:165], v[130:133], v[50:65]
	v_mfma_f32_32x32x16_bf16 v[18:33], v[162:165], v[146:149], v[18:33]
	v_mfma_f32_32x32x16_bf16 v[50:65], v[166:169], v[134:137], v[50:65]
	v_mfma_f32_32x32x16_bf16 v[18:33], v[166:169], v[150:153], v[18:33]
	v_mfma_f32_32x32x16_bf16 v[50:65], v[170:173], v[138:141], v[50:65]
	v_mfma_f32_32x32x16_bf16 v[18:33], v[170:173], v[154:157], v[18:33]
	v_mfma_f32_32x32x16_bf16 v[50:65], v[174:177], v[142:145], v[50:65]
	v_mfma_f32_32x32x16_bf16 v[18:33], v[174:177], v[158:161], v[18:33]
	v_mfma_f32_32x32x16_bf16 v[34:49], v[178:181], v[130:133], v[34:49]
	v_mfma_f32_32x32x16_bf16 v[2:17], v[178:181], v[146:149], v[2:17]
	v_mfma_f32_32x32x16_bf16 v[34:49], v[186:189], v[134:137], v[34:49]
	v_mfma_f32_32x32x16_bf16 v[2:17], v[186:189], v[150:153], v[2:17]
	v_mfma_f32_32x32x16_bf16 v[34:49], v[190:193], v[138:141], v[34:49]
	v_mfma_f32_32x32x16_bf16 v[2:17], v[190:193], v[154:157], v[2:17]
	v_mfma_f32_32x32x16_bf16 v[34:49], v[194:197], v[142:145], v[34:49]
	v_mfma_f32_32x32x16_bf16 v[2:17], v[194:197], v[158:161], v[2:17]
	s_barrier
	v_add3_u32 v242, v241, v236, s36
	v_add3_u32 v243, v241, v237, s36
	v_add3_u32 v244, v241, v238, s36
	v_add3_u32 v245, v241, v239, s36
	ds_read_b128 v[162:165], v242 offset:32768
	ds_read_b128 v[166:169], v243 offset:32768
	ds_read_b128 v[170:173], v244 offset:32768
	ds_read_b128 v[174:177], v245 offset:32768
	v_add3_u32 v242, v240, v236, s36
	v_add3_u32 v243, v240, v237, s36
	v_add3_u32 v244, v240, v238, s36
	v_add3_u32 v245, v240, v239, s36
	ds_read_b128 v[130:133], v242
	ds_read_b128 v[134:137], v243
	ds_read_b128 v[138:141], v244
	ds_read_b128 v[142:145], v245
	ds_read_b128 v[146:149], v242 offset:4096
	ds_read_b128 v[150:153], v243 offset:4096
	ds_read_b128 v[154:157], v244 offset:4096
	ds_read_b128 v[158:161], v245 offset:4096
	s_waitcnt vmcnt(2)
	s_barrier
	s_waitcnt lgkmcnt(0)
	v_mfma_f32_32x32x16_bf16 v[114:129], v[162:165], v[130:133], v[114:129]
	v_mfma_f32_32x32x16_bf16 v[82:97], v[162:165], v[146:149], v[82:97]
	v_mfma_f32_32x32x16_bf16 v[114:129], v[166:169], v[134:137], v[114:129]
	v_mfma_f32_32x32x16_bf16 v[82:97], v[166:169], v[150:153], v[82:97]
	v_mfma_f32_32x32x16_bf16 v[114:129], v[170:173], v[138:141], v[114:129]
	v_mfma_f32_32x32x16_bf16 v[82:97], v[170:173], v[154:157], v[82:97]
	v_mfma_f32_32x32x16_bf16 v[114:129], v[174:177], v[142:145], v[114:129]
	v_mfma_f32_32x32x16_bf16 v[82:97], v[174:177], v[158:161], v[82:97]
	s_barrier
	v_add3_u32 v242, v241, v236, s36
	v_add3_u32 v243, v241, v237, s36
	v_add3_u32 v244, v241, v238, s36
	v_add3_u32 v245, v241, v239, s36
	ds_read_b128 v[178:181], v242 offset:49152
	ds_read_b128 v[186:189], v243 offset:49152
	ds_read_b128 v[190:193], v244 offset:49152
	ds_read_b128 v[194:197], v245 offset:49152
	s_waitcnt vmcnt(0)
	s_barrier
	s_waitcnt lgkmcnt(0)
	v_mfma_f32_32x32x16_bf16 v[98:113], v[178:181], v[130:133], v[98:113]
	v_mfma_f32_32x32x16_bf16 v[66:81], v[178:181], v[146:149], v[66:81]
	v_mfma_f32_32x32x16_bf16 v[98:113], v[186:189], v[134:137], v[98:113]
	v_mfma_f32_32x32x16_bf16 v[66:81], v[186:189], v[150:153], v[66:81]
	v_mfma_f32_32x32x16_bf16 v[98:113], v[190:193], v[138:141], v[98:113]
	v_mfma_f32_32x32x16_bf16 v[66:81], v[190:193], v[154:157], v[66:81]
	v_mfma_f32_32x32x16_bf16 v[98:113], v[194:197], v[142:145], v[98:113]
	v_mfma_f32_32x32x16_bf16 v[66:81], v[194:197], v[158:161], v[66:81]
	s_barrier
; template <bool SWAP>
; DI void gemm_mainloop(f32x16 (&acc)[4][2], const u16* __restrict__ A, int lda, int rlo, int rhi,
;                       const u16* __restrict__ B, int ldb, int K, char* lds, const u16* zero_line) {
;     ...
;     ldfrag(st, 3, 1);
;     mma(0);
;     pat_rd();
;     asm volatile("s_waitcnt vmcnt(0)" ::: "memory");
;     __syncthreads();
;   }
;   mma(1);
	v_add3_u32 v242, v240, v236, s36
	v_add3_u32 v243, v240, v237, s36
	v_add3_u32 v244, v240, v238, s36
	v_add3_u32 v245, v240, v239, s36
	ds_read_b128 v[130:133], v242 offset:16384
	ds_read_b128 v[134:137], v243 offset:16384
	ds_read_b128 v[138:141], v244 offset:16384
	ds_read_b128 v[142:145], v245 offset:16384
	ds_read_b128 v[146:149], v242 offset:20480
	ds_read_b128 v[150:153], v243 offset:20480
	ds_read_b128 v[154:157], v244 offset:20480
	ds_read_b128 v[158:161], v245 offset:20480
	s_barrier
	s_waitcnt lgkmcnt(0)
	v_mfma_f32_32x32x16_bf16 v[50:65], v[162:165], v[130:133], v[50:65]
	v_mfma_f32_32x32x16_bf16 v[18:33], v[162:165], v[146:149], v[18:33]
	v_mfma_f32_32x32x16_bf16 v[50:65], v[166:169], v[134:137], v[50:65]
	v_mfma_f32_32x32x16_bf16 v[18:33], v[166:169], v[150:153], v[18:33]
	v_mfma_f32_32x32x16_bf16 v[50:65], v[170:173], v[138:141], v[50:65]
	v_mfma_f32_32x32x16_bf16 v[18:33], v[170:173], v[154:157], v[18:33]
	v_mfma_f32_32x32x16_bf16 v[50:65], v[174:177], v[142:145], v[50:65]
	v_mfma_f32_32x32x16_bf16 v[18:33], v[174:177], v[158:161], v[18:33]
	v_mfma_f32_32x32x16_bf16 v[34:49], v[178:181], v[130:133], v[34:49]
	v_mfma_f32_32x32x16_bf16 v[2:17], v[178:181], v[146:149], v[2:17]
	v_mfma_f32_32x32x16_bf16 v[34:49], v[186:189], v[134:137], v[34:49]
	v_mfma_f32_32x32x16_bf16 v[2:17], v[186:189], v[150:153], v[2:17]
	v_mfma_f32_32x32x16_bf16 v[34:49], v[190:193], v[138:141], v[34:49]
	v_mfma_f32_32x32x16_bf16 v[2:17], v[190:193], v[154:157], v[2:17]
	v_mfma_f32_32x32x16_bf16 v[34:49], v[194:197], v[142:145], v[34:49]
	v_mfma_f32_32x32x16_bf16 v[2:17], v[194:197], v[158:161], v[2:17]
	s_barrier
	s_cmp_eq_u32 s101, 0
	s_cbranch_scc0 .Lg8_m246_p1
	s_barrier
; template <int EPI>
; DI void phase_gemm(const Params& p, const GemmArgs& ga, char* lds) {
;     ...
;     if (EPI == EPI_M) {
;       u16* mo = ga.Mout + (size_t)(tokbase + pos0 + wm * 128 + r) * DM + n0w + 8 * h;
; #pragma unroll
;       for (int mi = 0; mi < 4; ++mi)
; #pragma unroll
;         for (int ni = 0; ni < 2; ++ni)
; #pragma unroll
;           for (int jp = 0; jp < 2; ++jp) {
;             u32x2 X = {pk_bf16(acc[mi][ni][8 * jp], acc[mi][ni][8 * jp + 1]), pk_bf16(acc[mi][ni][8 * jp + 2], acc[mi][ni][8 * jp + 3])};
;             u32x2 Y = {pk_bf16(acc[mi][ni][8 * jp + 4], acc[mi][ni][8 * jp + 5]), pk_bf16(acc[mi][ni][8 * jp + 6], acc[mi][ni][8 * jp + 7])};
;             half_swap(X, Y);
;             u32x4 v = {X.x, X.y, Y.x, Y.y};
;             *(u32x4*)(mo + (size_t)(mi * 32) * DM + ni * 32 + 16 * jp) = v;
;           }
.Lg8_m246_p1:
	s_nop 7
	s_nop 7
	v_mov_b32_e32 v178, v246
	v_mov_b32_e32 v179, v247
	v_mov_b32_e32 v200, v248
	v_add_u32_e32 v0, s35, v203
	v_add_u32_e32 v180, s35, v202
	v_add_u32_e32 v162, v0, v228
	v_add_u32_e32 v166, v180, v228
	s_mov_b32 s6, 0x10000
	s_mov_b64 s[40:41], 0x3838900
	s_mov_b64 s[38:39], 0x3858900
	s_mov_b64 s[36:37], 0x27c0080
	v_add_u32_e32 v146, v0, v227
	s_waitcnt lgkmcnt(2)
	s_waitcnt lgkmcnt(2)
	v_add_u32_e32 v158, v180, v227
	v_add_u32_e32 v166, v0, v201
	v_add_u32_e32 v0, v0, v179
	s_waitcnt lgkmcnt(2)
	s_waitcnt lgkmcnt(2)
	v_add_u32_e32 v130, v180, v201
	s_waitcnt lgkmcnt(2)
	s_waitcnt lgkmcnt(2)
	v_add_u32_e32 v0, v180, v179
	v_mov_b32_e32 v179, v1
	v_add_u32_e32 v152, s34, v200
	v_ashrrev_i32_e32 v153, 31, v152
	v_or_b32_e32 v150, s24, v185
	v_lshlrev_b64 v[152:153], 11, v[152:153]
	v_lshl_add_u64 v[152:153], s[14:15], 0, v[152:153]
	v_ashrrev_i32_e32 v151, 31, v150
	v_lshl_add_u64 v[150:151], v[150:151], 1, v[152:153]
	v_lshl_add_u64 v[150:151], v[150:151], 0, v[178:179]
	s_waitcnt vmcnt(0)
	s_waitcnt lgkmcnt(0)
	s_barrier
	s_nop 10
	v_cvt_pk_bf16_f32 v82, v82, v83
	v_cvt_pk_bf16_f32 v83, v84, v85
	v_cvt_pk_bf16_f32 v84, v86, v87
	v_add_co_u32_e32 v86, vcc, s6, v150
	s_mov_b32 s6, 0x30000
	s_nop 0
	v_addc_co_u32_e32 v87, vcc, 0, v151, vcc
	v_cvt_pk_bf16_f32 v50, v50, v51
	v_cvt_pk_bf16_f32 v51, v52, v53
	v_cvt_pk_bf16_f32 v52, v54, v55
	v_add_co_u32_e32 v54, vcc, s84, v150
	v_cvt_pk_bf16_f32 v85, v88, v89
	s_nop 0
	v_addc_co_u32_e32 v55, vcc, 0, v151, vcc
	s_nop 3
	v_cvt_pk_bf16_f32 v114, v114, v115
	v_cvt_pk_bf16_f32 v115, v116, v117
	v_cvt_pk_bf16_f32 v116, v118, v119
	v_cvt_pk_bf16_f32 v117, v120, v121
	v_cvt_pk_bf16_f32 v53, v56, v57
	v_permlane32_swap_b32_e32 v114, v116
	s_nop 0
	v_cvt_pk_bf16_f32 v98, v98, v99
	v_cvt_pk_bf16_f32 v99, v100, v101
	v_cvt_pk_bf16_f32 v100, v102, v103
	v_cvt_pk_bf16_f32 v101, v104, v105
	v_permlane32_swap_b32_e32 v115, v117
	v_permlane32_swap_b32_e32 v98, v100
	s_nop 3
	v_cvt_pk_bf16_f32 v66, v66, v67
	v_cvt_pk_bf16_f32 v67, v68, v69
	v_cvt_pk_bf16_f32 v68, v70, v71
	v_cvt_pk_bf16_f32 v69, v72, v73
	v_permlane32_swap_b32_e32 v99, v101
	v_permlane32_swap_b32_e32 v82, v84
	s_nop 0
	v_cvt_pk_bf16_f32 v34, v34, v35
	v_cvt_pk_bf16_f32 v35, v36, v37
	v_cvt_pk_bf16_f32 v36, v38, v39
	v_cvt_pk_bf16_f32 v37, v40, v41
	v_permlane32_swap_b32_e32 v83, v85
	v_permlane32_swap_b32_e32 v66, v68
	s_nop 3
	v_cvt_pk_bf16_f32 v18, v18, v19
	v_cvt_pk_bf16_f32 v19, v20, v21
	v_cvt_pk_bf16_f32 v20, v22, v23
	v_cvt_pk_bf16_f32 v21, v24, v25
	v_add_co_u32_e32 v22, vcc, s6, v150
	v_permlane32_swap_b32_e32 v67, v69
	s_nop 1
	v_cvt_pk_bf16_f32 v2, v2, v3
	v_cvt_pk_bf16_f32 v3, v4, v5
	v_cvt_pk_bf16_f32 v4, v6, v7
	v_cvt_pk_bf16_f32 v5, v8, v9
	v_permlane32_swap_b32_e32 v50, v52
	v_permlane32_swap_b32_e32 v51, v53
	v_permlane32_swap_b32_e32 v34, v36
	v_permlane32_swap_b32_e32 v35, v37
	v_permlane32_swap_b32_e32 v18, v20
	v_permlane32_swap_b32_e32 v19, v21
	v_addc_co_u32_e32 v23, vcc, 0, v151, vcc
	v_permlane32_swap_b32_e32 v2, v4
	v_permlane32_swap_b32_e32 v3, v5
	global_store_dwordx4 v[150:151], v[114:117], off
	global_store_dwordx4 v[150:151], v[98:101], off offset:64
	global_store_dwordx4 v[86:87], v[82:85], off
	v_cvt_pk_bf16_f32 v114, v122, v123
	v_cvt_pk_bf16_f32 v115, v124, v125
	v_cvt_pk_bf16_f32 v116, v126, v127
	v_cvt_pk_bf16_f32 v117, v128, v129
	v_cvt_pk_bf16_f32 v98, v106, v107
	v_cvt_pk_bf16_f32 v99, v108, v109
	v_cvt_pk_bf16_f32 v100, v110, v111
	v_cvt_pk_bf16_f32 v101, v112, v113
	v_cvt_pk_bf16_f32 v82, v90, v91
	v_cvt_pk_bf16_f32 v83, v92, v93
	v_cvt_pk_bf16_f32 v84, v94, v95
	v_cvt_pk_bf16_f32 v85, v96, v97
	global_store_dwordx4 v[86:87], v[66:69], off offset:64
	global_store_dwordx4 v[54:55], v[50:53], off
	global_store_dwordx4 v[54:55], v[34:37], off offset:64
	v_cvt_pk_bf16_f32 v66, v74, v75
	v_cvt_pk_bf16_f32 v67, v76, v77
	v_cvt_pk_bf16_f32 v68, v78, v79
	v_cvt_pk_bf16_f32 v69, v80, v81
	v_cvt_pk_bf16_f32 v50, v58, v59
	v_cvt_pk_bf16_f32 v51, v60, v61
	v_cvt_pk_bf16_f32 v52, v62, v63
	v_cvt_pk_bf16_f32 v53, v64, v65
	v_cvt_pk_bf16_f32 v34, v42, v43
	v_cvt_pk_bf16_f32 v35, v44, v45
	v_cvt_pk_bf16_f32 v36, v46, v47
	v_cvt_pk_bf16_f32 v37, v48, v49
	global_store_dwordx4 v[22:23], v[18:21], off
	global_store_dwordx4 v[22:23], v[2:5], off offset:64
	v_permlane32_swap_b32_e32 v114, v116
	v_cvt_pk_bf16_f32 v18, v26, v27
	v_cvt_pk_bf16_f32 v19, v28, v29
	v_cvt_pk_bf16_f32 v20, v30, v31
	v_cvt_pk_bf16_f32 v21, v32, v33
	v_cvt_pk_bf16_f32 v2, v10, v11
	v_cvt_pk_bf16_f32 v3, v12, v13
	v_cvt_pk_bf16_f32 v4, v14, v15
	v_cvt_pk_bf16_f32 v5, v16, v17
	v_permlane32_swap_b32_e32 v115, v117
	v_permlane32_swap_b32_e32 v98, v100
	v_permlane32_swap_b32_e32 v99, v101
	v_permlane32_swap_b32_e32 v82, v84
	v_permlane32_swap_b32_e32 v83, v85
	v_permlane32_swap_b32_e32 v66, v68
	v_permlane32_swap_b32_e32 v67, v69
	v_permlane32_swap_b32_e32 v50, v52
	v_permlane32_swap_b32_e32 v51, v53
	v_permlane32_swap_b32_e32 v34, v36
	v_permlane32_swap_b32_e32 v35, v37
	v_permlane32_swap_b32_e32 v18, v20
	v_permlane32_swap_b32_e32 v19, v21
	v_permlane32_swap_b32_e32 v2, v4
	v_permlane32_swap_b32_e32 v3, v5
	global_store_dwordx4 v[150:151], v[114:117], off offset:32
	global_store_dwordx4 v[150:151], v[98:101], off offset:96
	global_store_dwordx4 v[86:87], v[82:85], off offset:32
	global_store_dwordx4 v[86:87], v[66:69], off offset:96
	global_store_dwordx4 v[54:55], v[50:53], off offset:32
	global_store_dwordx4 v[54:55], v[34:37], off offset:96
	global_store_dwordx4 v[22:23], v[18:21], off offset:32
	global_store_dwordx4 v[22:23], v[2:5], off offset:96
	s_branch .LBB0_243
